# norm phase: gain/scale/shift vectors of all four column groups of a row fetched together instead of one dependent round trip per group
# speedup vs baseline: 1.0355x; 1.0006x over previous
; __device__ __forceinline__ unsigned cvt_pk_bf16(float lo, float hi) { unsigned r; asm volatile("v_cvt_pk_bf16_f32 %0, %1, %2" : "=v"(r) : "v"(lo), "v"(hi)); return r; }
; __device__ __forceinline__ void norm_phase(const float* xs_lat, const float* xs_ctx, const float* partA, const float* partB, float* xc_wr, int row_begin, int rows, const float* gain, const float* modl, int shoff, int scoff, bf16_t* H, int gw, int NGW, int lane) {
;     ...
;             float s = 0.f;
; #pragma unroll
;             for (int j = 0; j < 4; ++j) s += (v[u][j][0] * v[u][j][0] + v[u][j][1] * v[u][j][1]) + (v[u][j][2] * v[u][j][2] + v[u][j][3] * v[u][j][3]);
;             const float rstd = 1.0f / sqrtf(wave_sum(s) * (1.f / D) + EPS);
;             const float* mb = modl + (size_t)b * NMOD;
;             u32x2* o8 = (u32x2*)(H + (size_t)row * D) + lane;
; #pragma unroll
;             for (int j = 0; j < 4; ++j) { const int c = 4 * (lane + 64 * j);
;                 const f32x4 g4 = *(const f32x4*)(gain + c), sc4 = *(const f32x4*)(mb + scoff + c), sh4 = *(const f32x4*)(mb + shoff + c);
;                 const f32x4 y = (v[u][j] * rstd * g4) * (sc4 + 1.0f) + sh4;
;                 u32x2 w; w.x = cvt_pk_bf16(y[0], y[1]); w.y = cvt_pk_bf16(y[2], y[3]); o8[64 * j] = w; }
.LBB0_1158:
	s_ashr_i32 s4, s24, 11
	v_pk_mul_f32 v[16:17], v[6:7], v[6:7]
	v_pk_mul_f32 v[18:19], v[4:5], v[4:5]
	s_mul_i32 s22, s4, 0x1800
	s_mul_hi_i32 s23, s4, 0x1800
	s_and_b64 s[4:5], s[30:31], exec
	v_pk_mov_b32 v[20:21], v[18:19], v[16:17] op_sel:[1,0]
	v_mov_b32_e32 v19, v17
	s_cselect_b32 s5, s23, 0
	s_cselect_b32 s4, s22, 0xc000
	v_pk_add_f32 v[16:17], v[20:21], v[18:19]
	s_lshl_b64 s[4:5], s[4:5], 2
	v_pk_add_f32 v[16:17], v[16:17], v[16:17] op_sel_hi:[0,1]
	v_pk_mul_f32 v[18:19], v[10:11], v[10:11]
	v_pk_mul_f32 v[20:21], v[8:9], v[8:9]
	s_add_u32 s4, s36, s4
	v_pk_mov_b32 v[22:23], v[20:21], v[18:19] op_sel:[1,0]
	v_mov_b32_e32 v21, v19
	v_mul_f32_e32 v16, v0, v0
	s_addc_u32 s5, s37, s5
	v_pk_add_f32 v[18:19], v[22:23], v[20:21]
	v_pk_fma_f32 v[20:21], v[0:1], v[0:1], v[16:17] op_sel_hi:[1,1,0]
	v_mul_f32_e32 v16, v2, v2
	s_add_u32 s22, s4, s0
	v_pk_add_f32 v[18:19], v[18:19], v[18:19] op_sel_hi:[0,1]
	v_pk_fma_f32 v[22:23], v[2:3], v[2:3], v[16:17] op_sel_hi:[1,1,0]
	s_addc_u32 s23, s5, 0
	v_mul_f32_e32 v20, v12, v12
	v_mul_f32_e32 v22, v13, v13
	v_mul_f32_e32 v18, v14, v14
	v_mul_f32_e32 v16, v15, v15
	s_add_u32 s30, s4, s1
	v_pk_add_f32 v[28:29], v[20:21], v[22:23]
	v_pk_add_f32 v[30:31], v[18:19], v[16:17]
	global_load_dwordx4 v[16:19], v[34:35], off
	global_load_dwordx4 v[20:23], v63, s[22:23]
	s_addc_u32 s31, s5, 0
	global_load_dwordx4 v[24:27], v63, s[30:31]
	global_load_dwordx4 v[132:135], v[36:37], off
	global_load_dwordx4 v[136:139], v64, s[22:23]
	global_load_dwordx4 v[140:143], v64, s[30:31]
	global_load_dwordx4 v[144:147], v[38:39], off
	global_load_dwordx4 v[148:151], v65, s[22:23]
	global_load_dwordx4 v[152:155], v65, s[30:31]
	global_load_dwordx4 v[160:163], v[40:41], off
	global_load_dwordx4 v[164:167], v66, s[22:23]
	global_load_dwordx4 v[168:171], v66, s[30:31]
	v_pk_add_f32 v[28:29], v[28:29], v[30:31]
	s_waitcnt vmcnt(1)
	v_pk_add_f32 v[20:21], v[20:21], 1.0 op_sel_hi:[1,0]
	v_add_f32_e32 v28, v28, v29
	ds_bpermute_b32 v29, v33, v28
	v_pk_add_f32 v[22:23], v[22:23], 1.0 op_sel_hi:[1,0]
	s_waitcnt lgkmcnt(0)
	v_add_f32_e32 v28, v28, v29
	ds_bpermute_b32 v29, v58, v28
	s_waitcnt lgkmcnt(0)
	v_add_f32_e32 v28, v28, v29
	ds_bpermute_b32 v29, v59, v28
	s_waitcnt lgkmcnt(0)
	v_add_f32_e32 v28, v28, v29
	ds_bpermute_b32 v29, v60, v28
	s_waitcnt lgkmcnt(0)
	v_add_f32_e32 v28, v28, v29
	ds_bpermute_b32 v29, v61, v28
	s_waitcnt lgkmcnt(0)
	v_add_f32_e32 v28, v28, v29
	ds_bpermute_b32 v29, v62, v28
	s_waitcnt lgkmcnt(0)
	v_add_f32_e32 v28, v28, v29
	v_fmamk_f32 v28, v28, 0x3a800000, v221
	v_mul_f32_e32 v29, 0x4f800000, v28
	v_cmp_gt_f32_e32 vcc, s83, v28
	s_nop 1
	v_cndmask_b32_e32 v28, v28, v29, vcc
	v_sqrt_f32_e32 v29, v28
	s_nop 0
	v_add_u32_e32 v30, -1, v29
	v_add_u32_e32 v31, 1, v29
	v_fma_f32 v52, -v30, v29, v28
	v_fma_f32 v53, -v31, v29, v28
	v_cmp_ge_f32_e64 s[4:5], 0, v52
	s_nop 1
	v_cndmask_b32_e64 v29, v29, v30, s[4:5]
	v_cmp_lt_f32_e64 s[4:5], 0, v53
	s_nop 1
	v_cndmask_b32_e64 v29, v29, v31, s[4:5]
	v_mul_f32_e32 v30, 0x37800000, v29
	v_cndmask_b32_e32 v29, v29, v30, vcc
	v_cmp_class_f32_e32 vcc, v28, v222
	s_nop 1
	v_cndmask_b32_e32 v30, v29, v28, vcc
	v_div_scale_f32 v31, s[4:5], v30, v30, 1.0
	v_rcp_f32_e32 v52, v31
	v_div_scale_f32 v53, vcc, 1.0, v30, 1.0
	v_lshl_add_u64 v[28:29], s[14:15], 0, v[96:97]
	v_fma_f32 v54, -v31, v52, 1.0
	v_fmac_f32_e32 v52, v54, v52
	v_mul_f32_e32 v54, v53, v52
	v_fma_f32 v55, -v31, v54, v53
	v_fmac_f32_e32 v54, v55, v52
	v_fma_f32 v31, -v31, v54, v53
	v_div_fmas_f32 v31, v31, v52, v54
	v_div_fixup_f32 v30, v31, v30, 1.0
	v_pk_mul_f32 v[54:55], v[4:5], v[30:31] op_sel_hi:[1,0]
	s_mov_b32 s4, 0x7000000
	v_pk_mul_f32 v[52:53], v[6:7], v[30:31] op_sel_hi:[1,0]
	v_pk_mul_f32 v[16:17], v[16:17], v[54:55]
	v_add_co_u32_e32 v28, vcc, s4, v28
	v_pk_mul_f32 v[18:19], v[18:19], v[52:53]
	s_waitcnt vmcnt(0)
	v_pk_fma_f32 v[16:17], v[20:21], v[16:17], v[24:25]
	v_addc_co_u32_e32 v29, vcc, 0, v29, vcc
	v_pk_fma_f32 v[18:19], v[22:23], v[18:19], v[26:27]
	v_cvt_pk_bf16_f32 v16, v16, v17
	v_pk_mul_f32 v[54:55], v[8:9], v[30:31] op_sel_hi:[1,0]
	v_cvt_pk_bf16_f32 v17, v18, v19
	global_store_dwordx2 v[28:29], v[16:17], off
	v_mov_b64_e32 v[16:17], v[132:133]
	v_mov_b64_e32 v[18:19], v[134:135]
	s_nop 0
	v_mov_b64_e32 v[20:21], v[136:137]
	v_mov_b64_e32 v[22:23], v[138:139]
	v_mov_b64_e32 v[24:25], v[140:141]
	v_mov_b64_e32 v[26:27], v[142:143]
	v_pk_mul_f32 v[52:53], v[10:11], v[30:31] op_sel_hi:[1,0]
	v_pk_mul_f32 v[16:17], v[16:17], v[54:55]
	v_pk_add_f32 v[20:21], v[20:21], 1.0 op_sel_hi:[1,0]
	v_pk_mul_f32 v[18:19], v[18:19], v[52:53]
	v_pk_add_f32 v[22:23], v[22:23], 1.0 op_sel_hi:[1,0]
	v_pk_fma_f32 v[16:17], v[20:21], v[16:17], v[24:25]
	v_pk_fma_f32 v[18:19], v[22:23], v[18:19], v[26:27]
	v_cvt_pk_bf16_f32 v16, v16, v17
	v_pk_mul_f32 v[54:55], v[0:1], v[30:31] op_sel_hi:[1,0]
	v_cvt_pk_bf16_f32 v17, v18, v19
	global_store_dwordx2 v[28:29], v[16:17], off offset:512
	v_mov_b64_e32 v[16:17], v[144:145]
	v_mov_b64_e32 v[18:19], v[146:147]
	s_nop 0
	v_mov_b64_e32 v[20:21], v[148:149]
	v_mov_b64_e32 v[22:23], v[150:151]
	v_mov_b64_e32 v[24:25], v[152:153]
	v_mov_b64_e32 v[26:27], v[154:155]
	v_pk_mul_f32 v[52:53], v[2:3], v[30:31] op_sel_hi:[1,0]
	v_pk_mul_f32 v[16:17], v[16:17], v[54:55]
	v_pk_add_f32 v[20:21], v[20:21], 1.0 op_sel_hi:[1,0]
	v_pk_mul_f32 v[18:19], v[18:19], v[52:53]
	v_pk_add_f32 v[22:23], v[22:23], 1.0 op_sel_hi:[1,0]
	v_pk_fma_f32 v[16:17], v[20:21], v[16:17], v[24:25]
	v_pk_fma_f32 v[18:19], v[22:23], v[18:19], v[26:27]
	v_cvt_pk_bf16_f32 v16, v16, v17
	v_pk_mul_f32 v[52:53], v[14:15], v[30:31] op_sel_hi:[1,0]
	v_cvt_pk_bf16_f32 v17, v18, v19
	global_store_dwordx2 v[28:29], v[16:17], off offset:1024
	v_mov_b64_e32 v[16:17], v[160:161]
	v_mov_b64_e32 v[18:19], v[162:163]
	s_nop 0
	v_mov_b64_e32 v[20:21], v[164:165]
	v_mov_b64_e32 v[22:23], v[166:167]
	v_mov_b64_e32 v[24:25], v[168:169]
	v_mov_b64_e32 v[26:27], v[170:171]
	v_pk_mul_f32 v[30:31], v[12:13], v[30:31] op_sel_hi:[1,0]
	v_pk_mul_f32 v[18:19], v[52:53], v[18:19]
	v_pk_mul_f32 v[16:17], v[30:31], v[16:17]
	v_pk_add_f32 v[20:21], v[20:21], 1.0 op_sel_hi:[1,0]
	v_pk_add_f32 v[22:23], v[22:23], 1.0 op_sel_hi:[1,0]
	v_pk_fma_f32 v[16:17], v[16:17], v[20:21], v[24:25]
	v_pk_fma_f32 v[18:19], v[18:19], v[22:23], v[26:27]
	v_cvt_pk_bf16_f32 v16, v16, v17
	s_nop 0
	v_cvt_pk_bf16_f32 v17, v18, v19
	global_store_dwordx2 v[28:29], v[16:17], off offset:1536

; __device__ __forceinline__ unsigned cvt_pk_bf16(float lo, float hi) { unsigned r; asm volatile("v_cvt_pk_bf16_f32 %0, %1, %2" : "=v"(r) : "v"(lo), "v"(hi)); return r; }
; __device__ __forceinline__ void norm_phase(const float* xs_lat, const float* xs_ctx, const float* partA, const float* partB, float* xc_wr, int row_begin, int rows, const float* gain, const float* modl, int shoff, int scoff, bf16_t* H, int gw, int NGW, int lane) {
;     ...
;             float s = 0.f;
; #pragma unroll
;             for (int j = 0; j < 4; ++j) s += (v[u][j][0] * v[u][j][0] + v[u][j][1] * v[u][j][1]) + (v[u][j][2] * v[u][j][2] + v[u][j][3] * v[u][j][3]);
;             const float rstd = 1.0f / sqrtf(wave_sum(s) * (1.f / D) + EPS);
;             const float* mb = modl + (size_t)b * NMOD;
;             u32x2* o8 = (u32x2*)(H + (size_t)row * D) + lane;
; #pragma unroll
;             for (int j = 0; j < 4; ++j) { const int c = 4 * (lane + 64 * j);
;                 const f32x4 g4 = *(const f32x4*)(gain + c), sc4 = *(const f32x4*)(mb + scoff + c), sh4 = *(const f32x4*)(mb + shoff + c);
;                 const f32x4 y = (v[u][j] * rstd * g4) * (sc4 + 1.0f) + sh4;
;                 u32x2 w; w.x = cvt_pk_bf16(y[0], y[1]); w.y = cvt_pk_bf16(y[2], y[3]); o8[64 * j] = w; }
.LBB0_1164:
	s_waitcnt vmcnt(3)
	v_pk_mul_f32 v[52:53], v[22:23], v[22:23]
	v_pk_mul_f32 v[54:55], v[20:21], v[20:21]
	s_ashr_i32 s22, s3, 11
	v_pk_mov_b32 v[56:57], v[54:55], v[52:53] op_sel:[1,0]
	v_mov_b32_e32 v55, v53
	v_pk_add_f32 v[52:53], v[56:57], v[54:55]
	s_waitcnt vmcnt(2)
	v_pk_mul_f32 v[54:55], v[30:31], v[30:31]
	v_pk_add_f32 v[52:53], v[52:53], v[52:53] op_sel_hi:[0,1]
	v_pk_mul_f32 v[56:57], v[28:29], v[28:29]
	s_waitcnt vmcnt(1)
	v_mul_f32_e32 v52, v16, v16
	v_pk_mov_b32 v[68:69], v[56:57], v[54:55] op_sel:[1,0]
	v_mov_b32_e32 v57, v55
	v_pk_add_f32 v[54:55], v[68:69], v[56:57]
	v_pk_fma_f32 v[56:57], v[16:17], v[16:17], v[52:53] op_sel_hi:[1,1,0]
	v_mul_f32_e32 v52, v18, v18
	v_pk_add_f32 v[54:55], v[54:55], v[54:55] op_sel_hi:[0,1]
	v_pk_fma_f32 v[68:69], v[18:19], v[18:19], v[52:53] op_sel_hi:[1,1,0]
	s_waitcnt vmcnt(0)
	v_mul_f32_e32 v56, v24, v24
	v_mul_f32_e32 v68, v25, v25
	v_mul_f32_e32 v54, v26, v26
	v_mul_f32_e32 v52, v27, v27
	v_pk_add_f32 v[56:57], v[56:57], v[68:69]
	v_pk_add_f32 v[52:53], v[54:55], v[52:53]
	s_mul_i32 s23, s22, 0x1800
	v_pk_add_f32 v[52:53], v[56:57], v[52:53]
	s_mul_hi_i32 s22, s22, 0x1800
	v_add_f32_e32 v52, v52, v53
	ds_bpermute_b32 v53, v33, v52
	v_lshl_add_u64 v[76:77], s[16:17], 0, v[96:97]
	s_mov_b32 s25, 0x7000000
	s_waitcnt lgkmcnt(0)
	v_add_f32_e32 v52, v52, v53
	ds_bpermute_b32 v53, v58, v52
	s_waitcnt lgkmcnt(0)
	v_add_f32_e32 v52, v52, v53
	ds_bpermute_b32 v53, v59, v52
	s_waitcnt lgkmcnt(0)
	v_add_f32_e32 v52, v52, v53
	ds_bpermute_b32 v53, v60, v52
	s_waitcnt lgkmcnt(0)
	v_add_f32_e32 v52, v52, v53
	ds_bpermute_b32 v53, v61, v52
	s_waitcnt lgkmcnt(0)
	v_add_f32_e32 v52, v52, v53
	ds_bpermute_b32 v53, v62, v52
	s_waitcnt lgkmcnt(0)
	v_add_f32_e32 v52, v52, v53
	v_fmamk_f32 v52, v52, 0x3a800000, v221
	v_cmp_gt_f32_e32 vcc, s83, v52
	v_mul_f32_e32 v53, 0x4f800000, v52
	s_nop 0
	v_cndmask_b32_e32 v52, v52, v53, vcc
	v_sqrt_f32_e32 v53, v52
	s_nop 0
	v_add_u32_e32 v54, -1, v53
	v_fma_f32 v55, -v54, v53, v52
	v_cmp_ge_f32_e64 s[4:5], 0, v55
	v_add_u32_e32 v55, 1, v53
	s_nop 0
	v_cndmask_b32_e64 v54, v53, v54, s[4:5]
	v_fma_f32 v53, -v55, v53, v52
	v_cmp_lt_f32_e64 s[4:5], 0, v53
	s_nop 1
	v_cndmask_b32_e64 v53, v54, v55, s[4:5]
	v_mul_f32_e32 v54, 0x37800000, v53
	v_cndmask_b32_e32 v53, v53, v54, vcc
	v_cmp_class_f32_e32 vcc, v52, v222
	s_and_b64 s[4:5], s[42:43], exec
	s_nop 0
	v_cndmask_b32_e32 v52, v53, v52, vcc
	v_div_scale_f32 v53, s[4:5], v52, v52, 1.0
	v_rcp_f32_e32 v54, v53
	s_cselect_b32 s5, s22, 0
	s_cselect_b32 s4, s23, 0xc000
	s_lshl_b64 s[4:5], s[4:5], 2
	v_fma_f32 v55, -v53, v54, 1.0
	v_fmac_f32_e32 v54, v55, v54
	v_div_scale_f32 v55, vcc, 1.0, v52, 1.0
	s_add_u32 s22, s36, s4
	v_mul_f32_e32 v56, v55, v54
	s_addc_u32 s23, s37, s5
	v_fma_f32 v57, -v53, v56, v55
	s_add_u32 s4, s22, s0
	v_fmac_f32_e32 v56, v57, v54
	s_addc_u32 s5, s23, 0
	v_fma_f32 v53, -v53, v56, v55
	s_add_u32 s22, s22, s1
	v_div_fmas_f32 v53, v53, v54, v56
	s_addc_u32 s23, s23, 0
	global_load_dwordx4 v[54:57], v[34:35], off
	global_load_dwordx4 v[68:71], v63, s[4:5]
	global_load_dwordx4 v[72:75], v63, s[22:23]
	global_load_dwordx4 v[132:135], v[36:37], off
	global_load_dwordx4 v[136:139], v64, s[4:5]
	global_load_dwordx4 v[140:143], v64, s[22:23]
	global_load_dwordx4 v[144:147], v[38:39], off
	global_load_dwordx4 v[148:151], v65, s[4:5]
	global_load_dwordx4 v[152:155], v65, s[22:23]
	global_load_dwordx4 v[160:163], v[40:41], off
	global_load_dwordx4 v[164:167], v66, s[4:5]
	global_load_dwordx4 v[168:171], v66, s[22:23]
	v_div_fixup_f32 v52, v53, v52, 1.0
	v_pk_mul_f32 v[22:23], v[22:23], v[52:53] op_sel_hi:[1,0]
	v_pk_mul_f32 v[20:21], v[20:21], v[52:53] op_sel_hi:[1,0]
	v_pk_mul_f32 v[30:31], v[30:31], v[52:53] op_sel_hi:[1,0]
	v_pk_mul_f32 v[28:29], v[28:29], v[52:53] op_sel_hi:[1,0]
	v_pk_mul_f32 v[18:19], v[18:19], v[52:53] op_sel_hi:[1,0]
	v_pk_mul_f32 v[16:17], v[16:17], v[52:53] op_sel_hi:[1,0]
	v_pk_mul_f32 v[24:25], v[24:25], v[52:53] op_sel_hi:[1,0]
	v_pk_mul_f32 v[26:27], v[26:27], v[52:53] op_sel_hi:[1,0]
	s_waitcnt vmcnt(2)
	v_pk_mul_f32 v[20:21], v[54:55], v[20:21]
	v_pk_mul_f32 v[22:23], v[56:57], v[22:23]
	s_waitcnt vmcnt(1)
	v_pk_add_f32 v[56:57], v[68:69], 1.0 op_sel_hi:[1,0]
	v_pk_add_f32 v[54:55], v[70:71], 1.0 op_sel_hi:[1,0]
	s_waitcnt vmcnt(0)
	v_pk_fma_f32 v[20:21], v[56:57], v[20:21], v[72:73]
	v_add_co_u32_e32 v72, vcc, s25, v76
	v_pk_fma_f32 v[22:23], v[54:55], v[22:23], v[74:75]
	s_nop 0
	v_addc_co_u32_e32 v73, vcc, 0, v77, vcc
	v_cvt_pk_bf16_f32 v20, v20, v21
	v_cvt_pk_bf16_f32 v21, v22, v23
	global_store_dwordx2 v[72:73], v[20:21], off
	v_mov_b64_e32 v[20:21], v[132:133]
	v_mov_b64_e32 v[22:23], v[134:135]
	s_nop 0
	v_mov_b64_e32 v[54:55], v[136:137]
	v_mov_b64_e32 v[56:57], v[138:139]
	v_mov_b64_e32 v[68:69], v[140:141]
	v_mov_b64_e32 v[70:71], v[142:143]
	s_andn2_b64 vcc, exec, s[40:41]
	v_pk_mul_f32 v[20:21], v[20:21], v[28:29]
	v_pk_mul_f32 v[22:23], v[22:23], v[30:31]
	v_pk_add_f32 v[30:31], v[54:55], 1.0 op_sel_hi:[1,0]
	v_pk_add_f32 v[28:29], v[56:57], 1.0 op_sel_hi:[1,0]
	v_pk_fma_f32 v[20:21], v[30:31], v[20:21], v[68:69]
	v_pk_fma_f32 v[22:23], v[28:29], v[22:23], v[70:71]
	v_cvt_pk_bf16_f32 v20, v20, v21
	s_nop 0
	v_cvt_pk_bf16_f32 v21, v22, v23
	global_store_dwordx2 v[72:73], v[20:21], off offset:512
	v_mov_b64_e32 v[20:21], v[144:145]
	v_mov_b64_e32 v[22:23], v[146:147]
	s_nop 0
	v_mov_b64_e32 v[28:29], v[148:149]
	v_mov_b64_e32 v[30:31], v[150:151]
	v_mov_b64_e32 v[54:55], v[152:153]
	v_mov_b64_e32 v[56:57], v[154:155]
	v_pk_mul_f32 v[16:17], v[20:21], v[16:17]
	v_pk_mul_f32 v[18:19], v[22:23], v[18:19]
	v_pk_add_f32 v[22:23], v[28:29], 1.0 op_sel_hi:[1,0]
	v_pk_add_f32 v[20:21], v[30:31], 1.0 op_sel_hi:[1,0]
	v_pk_fma_f32 v[16:17], v[22:23], v[16:17], v[54:55]
	v_pk_fma_f32 v[18:19], v[20:21], v[18:19], v[56:57]
	v_cvt_pk_bf16_f32 v16, v16, v17
	s_nop 0
	v_cvt_pk_bf16_f32 v17, v18, v19
	global_store_dwordx2 v[72:73], v[16:17], off offset:1024
	v_mov_b64_e32 v[16:17], v[160:161]
	v_mov_b64_e32 v[18:19], v[162:163]
	s_nop 0
	v_mov_b64_e32 v[20:21], v[164:165]
	v_mov_b64_e32 v[22:23], v[166:167]
	v_mov_b64_e32 v[28:29], v[168:169]
	v_mov_b64_e32 v[30:31], v[170:171]
	v_pk_mul_f32 v[16:17], v[24:25], v[16:17]
	v_pk_add_f32 v[20:21], v[20:21], 1.0 op_sel_hi:[1,0]
	v_pk_mul_f32 v[18:19], v[26:27], v[18:19]
	v_pk_add_f32 v[22:23], v[22:23], 1.0 op_sel_hi:[1,0]
	v_pk_fma_f32 v[16:17], v[16:17], v[20:21], v[28:29]
	v_pk_fma_f32 v[18:19], v[18:19], v[22:23], v[30:31]
	v_cvt_pk_bf16_f32 v16, v16, v17
	s_nop 0
	v_cvt_pk_bf16_f32 v17, v18, v19
	global_store_dwordx2 v[72:73], v[16:17], off offset:1536
	s_cbranch_vccnz .LBB0_1159
; __device__ __forceinline__ void norm_phase(const float* xs_lat, const float* xs_ctx, const float* partA, const float* partB, float* xc_wr, int row_begin, int rows, const float* gain, const float* modl, int shoff, int scoff, bf16_t* H, int gw, int NGW, int lane) {
;     ...
;             if (!lat && partA != nullptr) {
;                 const size_t ro = (size_t)(row - ML) * D;
; #pragma unroll
;                 for (int j = 0; j < 4; ++j) { const int ix = 64 * j + lane;
;                     v[u][j] = (((v[u][j] + ((const f32x4*)(partA + ro))[ix]) + ((const f32x4*)(partA + (size_t)MC * D + ro))[ix]) + ((const f32x4*)(partB + ro))[ix]) + ((const f32x4*)(partB + (size_t)MC * D + ro))[ix];
;                     ((f32x4*)(xc_wr + ro))[ix] = v[u][j]; }
;             }
	s_or_b64 s[4:5], s[10:11], s[30:31]
	s_and_b64 vcc, exec, s[4:5]
	s_cbranch_vccnz .LBB0_1158
	s_add_i32 s34, s24, 0xffffc000
	s_lshl_b64 s[4:5], s[34:35], 12
	v_lshl_add_u64 v[26:27], v[42:43], 0, s[4:5]
	global_load_dwordx4 v[16:19], v[26:27], off
	v_lshl_add_u64 v[28:29], v[44:45], 0, s[4:5]
	s_waitcnt vmcnt(0)
	v_pk_add_f32 v[18:19], v[6:7], v[18:19]
	v_pk_add_f32 v[16:17], v[4:5], v[16:17]
	global_load_dwordx4 v[4:7], v[28:29], off
	s_waitcnt vmcnt(0)
	v_pk_add_f32 v[20:21], v[18:19], v[6:7]
	v_lshl_add_u64 v[18:19], v[46:47], 0, s[4:5]
	v_pk_add_f32 v[16:17], v[16:17], v[4:5]
	global_load_dwordx4 v[4:7], v[18:19], off
	s_waitcnt vmcnt(0)
	v_pk_add_f32 v[22:23], v[20:21], v[6:7]
	v_lshl_add_u64 v[20:21], v[48:49], 0, s[4:5]
	v_pk_add_f32 v[16:17], v[16:17], v[4:5]
	global_load_dwordx4 v[4:7], v[20:21], off
	s_waitcnt vmcnt(0)
	v_pk_add_f32 v[6:7], v[22:23], v[6:7]
	v_pk_add_f32 v[4:5], v[16:17], v[4:5]
	v_lshl_add_u64 v[16:17], v[50:51], 0, s[4:5]
	global_store_dwordx4 v[16:17], v[4:7], off
	global_load_dwordx4 v[22:25], v[26:27], off offset:1024
	s_waitcnt vmcnt(0)
	v_pk_add_f32 v[24:25], v[10:11], v[24:25]
	v_pk_add_f32 v[22:23], v[8:9], v[22:23]
	global_load_dwordx4 v[8:11], v[28:29], off offset:1024
	s_waitcnt vmcnt(0)
	v_pk_add_f32 v[24:25], v[24:25], v[10:11]
	v_pk_add_f32 v[22:23], v[22:23], v[8:9]
	global_load_dwordx4 v[8:11], v[18:19], off offset:1024
	s_waitcnt vmcnt(0)
	v_pk_add_f32 v[24:25], v[24:25], v[10:11]
	v_pk_add_f32 v[22:23], v[22:23], v[8:9]
	global_load_dwordx4 v[8:11], v[20:21], off offset:1024
	s_waitcnt vmcnt(0)
	v_pk_add_f32 v[10:11], v[24:25], v[10:11]
	v_pk_add_f32 v[8:9], v[22:23], v[8:9]
	global_store_dwordx4 v[16:17], v[8:11], off offset:1024
	global_load_dwordx4 v[22:25], v[26:27], off offset:2048
	s_waitcnt vmcnt(0)
	v_pk_add_f32 v[24:25], v[2:3], v[24:25]
	v_pk_add_f32 v[22:23], v[0:1], v[22:23]
	global_load_dwordx4 v[0:3], v[28:29], off offset:2048
	s_waitcnt vmcnt(0)
	v_pk_add_f32 v[24:25], v[24:25], v[2:3]
	v_pk_add_f32 v[22:23], v[22:23], v[0:1]
	global_load_dwordx4 v[0:3], v[18:19], off offset:2048
	s_waitcnt vmcnt(0)
	v_pk_add_f32 v[24:25], v[24:25], v[2:3]
	v_pk_add_f32 v[22:23], v[22:23], v[0:1]
	global_load_dwordx4 v[0:3], v[20:21], off offset:2048
	s_waitcnt vmcnt(0)
	v_pk_add_f32 v[2:3], v[24:25], v[2:3]
	v_pk_add_f32 v[0:1], v[22:23], v[0:1]
	global_store_dwordx4 v[16:17], v[0:3], off offset:2048
	global_load_dwordx4 v[22:25], v[26:27], off offset:3072
	s_waitcnt vmcnt(0)
	v_pk_add_f32 v[24:25], v[14:15], v[24:25]
	v_pk_add_f32 v[22:23], v[12:13], v[22:23]
	global_load_dwordx4 v[12:15], v[28:29], off offset:3072
	s_waitcnt vmcnt(0)
	v_pk_add_f32 v[24:25], v[24:25], v[14:15]
	v_pk_add_f32 v[22:23], v[22:23], v[12:13]
	global_load_dwordx4 v[12:15], v[18:19], off offset:3072
	s_waitcnt vmcnt(0)
	v_pk_add_f32 v[18:19], v[24:25], v[14:15]
	v_pk_add_f32 v[22:23], v[22:23], v[12:13]
	global_load_dwordx4 v[12:15], v[20:21], off offset:3072
	s_waitcnt vmcnt(0)
	v_pk_add_f32 v[14:15], v[18:19], v[14:15]
	v_pk_add_f32 v[12:13], v[22:23], v[12:13]
	global_store_dwordx4 v[16:17], v[12:15], off offset:3072
	s_branch .LBB0_1158
